# GEMM phases: accumulator clear before each unit's K loop with 64 v_mov_b64 instead of 128 v_mov_b32
# speedup vs baseline: 1.0077x; 1.0031x over previous
; template <class Epi, bool HOOK = false>
; DI void gemm_phase(LAS unsigned char* lds, const Gemm g, const StaticOrder& S, const Epi& E) {
;     ...
;         const char* nA = has_next ? (const char*)g.A + (size_t)nxt.pm * tstep : cA; const char* nB = has_next ? (const char*)g.Bt + (size_t)nxt.pn * tstep : cB;
;     ...
; #pragma unroll
;         for (int a = 0; a < 2; ++a)
; #pragma unroll
;             for (int b = 0; b < 2; ++b)
; #pragma unroll
;                 for (int m = 0; m < 4; ++m)
; #pragma unroll
;                     for (int n = 0; n < 2; ++n) acc[a][b][m][n] = (f32x4){0.f, 0.f, 0.f, 0.f};
.LBB0_232:
	s_ashr_i32 s37, s36, 31
	s_lshl_b64 s[40:41], s[36:37], 19
	s_add_u32 s40, s44, s40
	s_addc_u32 s41, s45, s41
	s_and_b64 s[48:49], s[4:5], exec
	s_cselect_b32 s31, s41, s51
	s_cselect_b32 s37, s40, s50
	s_ashr_i32 s35, s34, 31
	s_lshl_b64 s[48:49], s[34:35], 19
	s_add_u32 s48, s24, s48
	s_addc_u32 s49, s25, s49
	s_and_b64 s[54:55], s[4:5], exec
	s_cselect_b32 s35, s49, s53
	s_cselect_b32 s67, s48, s52
	s_add_u32 s50, s50, 0x40080
	s_addc_u32 s51, s51, 0
	s_add_u32 s68, s52, 0x100
	v_mov_b64_e32 v[2:3], 0
	s_addc_u32 s69, s53, 0
	s_mov_b32 s70, -2
	v_mov_b64_e32 v[4:5], 0
	v_mov_b64_e32 v[6:7], 0
	v_mov_b64_e32 v[8:9], 0
	v_mov_b64_e32 v[18:19], 0
	v_mov_b64_e32 v[20:21], 0
	v_mov_b64_e32 v[22:23], 0
	v_mov_b64_e32 v[24:25], 0
	v_mov_b64_e32 v[34:35], 0
	v_mov_b64_e32 v[36:37], 0
	v_mov_b64_e32 v[38:39], 0
	v_mov_b64_e32 v[40:41], 0
	v_mov_b64_e32 v[50:51], 0
	v_mov_b64_e32 v[52:53], 0
	v_mov_b64_e32 v[54:55], 0
	v_mov_b64_e32 v[56:57], 0
	v_mov_b64_e32 v[10:11], 0
	v_mov_b64_e32 v[12:13], 0
	v_mov_b64_e32 v[14:15], 0
	v_mov_b64_e32 v[16:17], 0
	v_mov_b64_e32 v[26:27], 0
	v_mov_b64_e32 v[28:29], 0
	v_mov_b64_e32 v[30:31], 0
	v_mov_b64_e32 v[32:33], 0
	v_mov_b64_e32 v[42:43], 0
	v_mov_b64_e32 v[44:45], 0
	v_mov_b64_e32 v[46:47], 0
	v_mov_b64_e32 v[48:49], 0
	v_mov_b64_e32 v[58:59], 0
	v_mov_b64_e32 v[60:61], 0
	v_mov_b64_e32 v[62:63], 0
	v_mov_b64_e32 v[64:65], 0
	v_mov_b64_e32 v[66:67], 0
	v_mov_b64_e32 v[68:69], 0
	v_mov_b64_e32 v[70:71], 0
	v_mov_b64_e32 v[72:73], 0
	v_mov_b64_e32 v[82:83], 0
	v_mov_b64_e32 v[84:85], 0
	v_mov_b64_e32 v[86:87], 0
	v_mov_b64_e32 v[88:89], 0
	v_mov_b64_e32 v[98:99], 0
	v_mov_b64_e32 v[100:101], 0
	v_mov_b64_e32 v[102:103], 0
	v_mov_b64_e32 v[104:105], 0
	v_mov_b64_e32 v[114:115], 0
	v_mov_b64_e32 v[116:117], 0
	v_mov_b64_e32 v[118:119], 0
	v_mov_b64_e32 v[120:121], 0
	v_mov_b64_e32 v[74:75], 0
	v_mov_b64_e32 v[76:77], 0
	v_mov_b64_e32 v[78:79], 0
	v_mov_b64_e32 v[80:81], 0
	v_mov_b64_e32 v[90:91], 0
	v_mov_b64_e32 v[92:93], 0
	v_mov_b64_e32 v[94:95], 0
	v_mov_b64_e32 v[96:97], 0
	v_mov_b64_e32 v[106:107], 0
	v_mov_b64_e32 v[108:109], 0
	v_mov_b64_e32 v[110:111], 0
	v_mov_b64_e32 v[112:113], 0
	v_mov_b64_e32 v[122:123], 0
	v_mov_b64_e32 v[124:125], 0
	v_mov_b64_e32 v[126:127], 0
	v_mov_b64_e32 v[128:129], 0

; template <class Epi, bool HOOK = false>
; DI void gemm_phase(LAS unsigned char* lds, const Gemm g, const StaticOrder& S, const Epi& E) {
;     ...
; #pragma unroll
;         for (int a = 0; a < 2; ++a)
; #pragma unroll
;             for (int b = 0; b < 2; ++b)
; #pragma unroll
;                 for (int m = 0; m < 4; ++m)
; #pragma unroll
;                     for (int n = 0; n < 2; ++n) acc[a][b][m][n] = (f32x4){0.f, 0.f, 0.f, 0.f};
.LBB0_869:
	v_mov_b64_e32 v[2:3], 0
	v_lshl_add_u64 v[130:131], s[60:61], 0, v[146:147]
	v_lshl_add_u64 v[132:133], s[60:61], 0, v[148:149]
	v_lshl_add_u64 v[134:135], s[58:59], 0, v[150:151]
	v_lshl_add_u64 v[136:137], s[58:59], 0, v[152:153]
	s_mov_b32 s51, -2
	s_mov_b64 s[54:55], 0
	v_mov_b64_e32 v[4:5], 0
	v_mov_b64_e32 v[6:7], 0
	v_mov_b64_e32 v[8:9], 0
	v_mov_b64_e32 v[18:19], 0
	v_mov_b64_e32 v[20:21], 0
	v_mov_b64_e32 v[22:23], 0
	v_mov_b64_e32 v[24:25], 0
	v_mov_b64_e32 v[42:43], 0
	v_mov_b64_e32 v[44:45], 0
	v_mov_b64_e32 v[46:47], 0
	v_mov_b64_e32 v[48:49], 0
	v_mov_b64_e32 v[94:95], 0
	v_mov_b64_e32 v[96:97], 0
	v_mov_b64_e32 v[98:99], 0
	v_mov_b64_e32 v[100:101], 0
	v_mov_b64_e32 v[10:11], 0
	v_mov_b64_e32 v[12:13], 0
	v_mov_b64_e32 v[14:15], 0
	v_mov_b64_e32 v[16:17], 0
	v_mov_b64_e32 v[26:27], 0
	v_mov_b64_e32 v[28:29], 0
	v_mov_b64_e32 v[38:39], 0
	v_mov_b64_e32 v[40:41], 0
	v_mov_b64_e32 v[86:87], 0
	v_mov_b64_e32 v[88:89], 0
	v_mov_b64_e32 v[90:91], 0
	v_mov_b64_e32 v[92:93], 0
	v_mov_b64_e32 v[118:119], 0
	v_mov_b64_e32 v[120:121], 0
	v_mov_b64_e32 v[122:123], 0
	v_mov_b64_e32 v[124:125], 0
	v_mov_b64_e32 v[126:127], 0
	v_mov_b64_e32 v[128:129], 0
	v_mov_b64_e32 v[114:115], 0
	v_mov_b64_e32 v[116:117], 0
	v_mov_b64_e32 v[102:103], 0
	v_mov_b64_e32 v[104:105], 0
	v_mov_b64_e32 v[82:83], 0
	v_mov_b64_e32 v[84:85], 0
	v_mov_b64_e32 v[78:79], 0
	v_mov_b64_e32 v[80:81], 0
	v_mov_b64_e32 v[66:67], 0
	v_mov_b64_e32 v[68:69], 0
	v_mov_b64_e32 v[62:63], 0
	v_mov_b64_e32 v[64:65], 0
	v_mov_b64_e32 v[50:51], 0
	v_mov_b64_e32 v[52:53], 0
	v_mov_b64_e32 v[106:107], 0
	v_mov_b64_e32 v[108:109], 0
	v_mov_b64_e32 v[110:111], 0
	v_mov_b64_e32 v[112:113], 0
	v_mov_b64_e32 v[70:71], 0
	v_mov_b64_e32 v[72:73], 0
	v_mov_b64_e32 v[74:75], 0
	v_mov_b64_e32 v[76:77], 0
	v_mov_b64_e32 v[54:55], 0
	v_mov_b64_e32 v[56:57], 0
	v_mov_b64_e32 v[58:59], 0
	v_mov_b64_e32 v[60:61], 0
	v_mov_b64_e32 v[30:31], 0
	v_mov_b64_e32 v[32:33], 0
	v_mov_b64_e32 v[34:35], 0
	v_mov_b64_e32 v[36:37], 0

; template <class Epi, bool HOOK = false>
; DI void gemm_phase(LAS unsigned char* lds, const Gemm g, const StaticOrder& S, const Epi& E) {
;     ...
;         const char* nA = has_next ? (const char*)g.A + (size_t)nxt.pm * tstep : cA; const char* nB = has_next ? (const char*)g.Bt + (size_t)nxt.pn * tstep : cB;
;     ...
; #pragma unroll
;         for (int a = 0; a < 2; ++a)
; #pragma unroll
;             for (int b = 0; b < 2; ++b)
; #pragma unroll
;                 for (int m = 0; m < 4; ++m)
; #pragma unroll
;                     for (int n = 0; n < 2; ++n) acc[a][b][m][n] = (f32x4){0.f, 0.f, 0.f, 0.f};
.LBB0_949:
	s_ashr_i32 s43, s42, 31
	s_lshl_b64 s[44:45], s[42:43], 19
	s_add_u32 s44, s10, s44
	s_addc_u32 s45, s11, s45
	s_and_b64 s[46:47], s[6:7], exec
	s_cselect_b32 s43, s45, s51
	s_cselect_b32 s49, s44, s50
	s_ashr_i32 s41, s40, 31
	s_lshl_b64 s[46:47], s[40:41], 19
	s_add_u32 s46, s36, s46
	s_addc_u32 s47, s37, s47
	s_and_b64 s[54:55], s[6:7], exec
	s_cselect_b32 s41, s47, s53
	s_cselect_b32 s65, s46, s52
	s_add_u32 s50, s50, 0x40080
	s_addc_u32 s51, s51, 0
	s_add_u32 s66, s52, 0x100
	v_mov_b64_e32 v[2:3], 0
	s_addc_u32 s67, s53, 0
	s_mov_b32 s68, -2
	s_waitcnt lgkmcnt(0)
	v_mov_b64_e32 v[4:5], 0
	v_mov_b64_e32 v[6:7], 0
	v_mov_b64_e32 v[8:9], 0
	v_mov_b64_e32 v[18:19], 0
	v_mov_b64_e32 v[20:21], 0
	v_mov_b64_e32 v[22:23], 0
	v_mov_b64_e32 v[24:25], 0
	v_mov_b64_e32 v[34:35], 0
	v_mov_b64_e32 v[36:37], 0
	v_mov_b64_e32 v[38:39], 0
	v_mov_b64_e32 v[40:41], 0
	v_mov_b64_e32 v[50:51], 0
	v_mov_b64_e32 v[52:53], 0
	v_mov_b64_e32 v[54:55], 0
	v_mov_b64_e32 v[56:57], 0
	v_mov_b64_e32 v[10:11], 0
	v_mov_b64_e32 v[12:13], 0
	v_mov_b64_e32 v[14:15], 0
	v_mov_b64_e32 v[16:17], 0
	v_mov_b64_e32 v[26:27], 0
	v_mov_b64_e32 v[28:29], 0
	v_mov_b64_e32 v[30:31], 0
	v_mov_b64_e32 v[32:33], 0
	v_mov_b64_e32 v[42:43], 0
	v_mov_b64_e32 v[44:45], 0
	v_mov_b64_e32 v[46:47], 0
	v_mov_b64_e32 v[48:49], 0
	v_mov_b64_e32 v[58:59], 0
	v_mov_b64_e32 v[60:61], 0
	v_mov_b64_e32 v[62:63], 0
	v_mov_b64_e32 v[64:65], 0
	v_mov_b64_e32 v[66:67], 0
	v_mov_b64_e32 v[68:69], 0
	v_mov_b64_e32 v[70:71], 0
	v_mov_b64_e32 v[72:73], 0
	v_mov_b64_e32 v[82:83], 0
	v_mov_b64_e32 v[84:85], 0
	v_mov_b64_e32 v[86:87], 0
	v_mov_b64_e32 v[88:89], 0
	v_mov_b64_e32 v[98:99], 0
	v_mov_b64_e32 v[100:101], 0
	v_mov_b64_e32 v[102:103], 0
	v_mov_b64_e32 v[104:105], 0
	v_mov_b64_e32 v[114:115], 0
	v_mov_b64_e32 v[116:117], 0
	v_mov_b64_e32 v[118:119], 0
	v_mov_b64_e32 v[120:121], 0
	v_mov_b64_e32 v[74:75], 0
	v_mov_b64_e32 v[76:77], 0
	v_mov_b64_e32 v[78:79], 0
	v_mov_b64_e32 v[80:81], 0
	v_mov_b64_e32 v[90:91], 0
	v_mov_b64_e32 v[92:93], 0
	v_mov_b64_e32 v[94:95], 0
	v_mov_b64_e32 v[96:97], 0
	v_mov_b64_e32 v[106:107], 0
	v_mov_b64_e32 v[108:109], 0
	v_mov_b64_e32 v[110:111], 0
	v_mov_b64_e32 v[112:113], 0
	v_mov_b64_e32 v[122:123], 0
	v_mov_b64_e32 v[124:125], 0
	v_mov_b64_e32 v[126:127], 0
	v_mov_b64_e32 v[128:129], 0

; template <class Epi, bool HOOK = false>
; DI void gemm_phase(LAS unsigned char* lds, const Gemm g, const StaticOrder& S, const Epi& E) {
;     ...
;         const char* nA = has_next ? (const char*)g.A + (size_t)nxt.pm * tstep : cA; const char* nB = has_next ? (const char*)g.Bt + (size_t)nxt.pn * tstep : cB;
;     ...
; #pragma unroll
;         for (int a = 0; a < 2; ++a)
; #pragma unroll
;             for (int b = 0; b < 2; ++b)
; #pragma unroll
;                 for (int m = 0; m < 4; ++m)
; #pragma unroll
;                     for (int n = 0; n < 2; ++n) acc[a][b][m][n] = (f32x4){0.f, 0.f, 0.f, 0.f};
.LBB0_1033:
	s_ashr_i32 s29, s28, 31
	s_lshl_b64 s[36:37], s[28:29], 19
	s_add_u32 s36, s12, s36
	s_addc_u32 s37, s13, s37
	s_and_b64 s[38:39], s[4:5], exec
	s_cselect_b32 s29, s37, s41
	s_cselect_b32 s59, s36, s40
	s_ashr_i32 s27, s26, 31
	s_lshl_b64 s[38:39], s[26:27], 19
	s_add_u32 s38, s34, s38
	s_addc_u32 s39, s35, s39
	s_and_b64 s[44:45], s[4:5], exec
	s_cselect_b32 s27, s39, s43
	s_cselect_b32 s60, s38, s42
	s_add_u32 s40, s40, 0x40080
	s_addc_u32 s41, s41, 0
	s_add_u32 s61, s42, 0x100
	v_mov_b64_e32 v[2:3], 0
	s_addc_u32 s62, s43, 0
	s_mov_b32 s63, -2
	v_mov_b64_e32 v[4:5], 0
	v_mov_b64_e32 v[6:7], 0
	v_mov_b64_e32 v[8:9], 0
	v_mov_b64_e32 v[18:19], 0
	v_mov_b64_e32 v[20:21], 0
	v_mov_b64_e32 v[22:23], 0
	v_mov_b64_e32 v[24:25], 0
	v_mov_b64_e32 v[34:35], 0
	v_mov_b64_e32 v[36:37], 0
	v_mov_b64_e32 v[38:39], 0
	v_mov_b64_e32 v[40:41], 0
	v_mov_b64_e32 v[50:51], 0
	v_mov_b64_e32 v[52:53], 0
	v_mov_b64_e32 v[54:55], 0
	v_mov_b64_e32 v[56:57], 0
	v_mov_b64_e32 v[10:11], 0
	v_mov_b64_e32 v[12:13], 0
	v_mov_b64_e32 v[14:15], 0
	v_mov_b64_e32 v[16:17], 0
	v_mov_b64_e32 v[26:27], 0
	v_mov_b64_e32 v[28:29], 0
	v_mov_b64_e32 v[30:31], 0
	v_mov_b64_e32 v[32:33], 0
	v_mov_b64_e32 v[42:43], 0
	v_mov_b64_e32 v[44:45], 0
	v_mov_b64_e32 v[46:47], 0
	v_mov_b64_e32 v[48:49], 0
	v_mov_b64_e32 v[58:59], 0
	v_mov_b64_e32 v[60:61], 0
	v_mov_b64_e32 v[62:63], 0
	v_mov_b64_e32 v[64:65], 0
	v_mov_b64_e32 v[66:67], 0
	v_mov_b64_e32 v[68:69], 0
	v_mov_b64_e32 v[70:71], 0
	v_mov_b64_e32 v[72:73], 0
	v_mov_b64_e32 v[82:83], 0
	v_mov_b64_e32 v[84:85], 0
	v_mov_b64_e32 v[86:87], 0
	v_mov_b64_e32 v[88:89], 0
	v_mov_b64_e32 v[98:99], 0
	v_mov_b64_e32 v[100:101], 0
	v_mov_b64_e32 v[102:103], 0
	v_mov_b64_e32 v[104:105], 0
	v_mov_b64_e32 v[114:115], 0
	v_mov_b64_e32 v[116:117], 0
	v_mov_b64_e32 v[118:119], 0
	v_mov_b64_e32 v[120:121], 0
	v_mov_b64_e32 v[74:75], 0
	v_mov_b64_e32 v[76:77], 0
	v_mov_b64_e32 v[78:79], 0
	v_mov_b64_e32 v[80:81], 0
	v_mov_b64_e32 v[90:91], 0
	v_mov_b64_e32 v[92:93], 0
	v_mov_b64_e32 v[94:95], 0
	v_mov_b64_e32 v[96:97], 0
	v_mov_b64_e32 v[106:107], 0
	v_mov_b64_e32 v[108:109], 0
	v_mov_b64_e32 v[110:111], 0
	v_mov_b64_e32 v[112:113], 0
	v_mov_b64_e32 v[122:123], 0
	v_mov_b64_e32 v[124:125], 0
	v_mov_b64_e32 v[126:127], 0
	v_mov_b64_e32 v[128:129], 0

; template <class Epi, bool HOOK = false>
; DI void gemm_phase(LAS unsigned char* lds, const Gemm g, const StaticOrder& S, const Epi& E) {
;     ...
; #pragma unroll
;         for (int a = 0; a < 2; ++a)
; #pragma unroll
;             for (int b = 0; b < 2; ++b)
; #pragma unroll
;                 for (int m = 0; m < 4; ++m)
; #pragma unroll
;                     for (int n = 0; n < 2; ++n) acc[a][b][m][n] = (f32x4){0.f, 0.f, 0.f, 0.f};
.LBB0_1113:
	s_add_u32 s39, s42, 0x100
	v_mov_b64_e32 v[0:1], 0
	s_addc_u32 s62, s43, 0
	s_mov_b32 s63, -2
	v_mov_b64_e32 v[2:3], 0
	v_mov_b64_e32 v[4:5], 0
	v_mov_b64_e32 v[6:7], 0
	v_mov_b64_e32 v[16:17], 0
	v_mov_b64_e32 v[18:19], 0
	v_mov_b64_e32 v[20:21], 0
	v_mov_b64_e32 v[22:23], 0
	v_mov_b64_e32 v[32:33], 0
	v_mov_b64_e32 v[34:35], 0
	v_mov_b64_e32 v[36:37], 0
	v_mov_b64_e32 v[38:39], 0
	v_mov_b64_e32 v[48:49], 0
	v_mov_b64_e32 v[50:51], 0
	v_mov_b64_e32 v[52:53], 0
	v_mov_b64_e32 v[54:55], 0
	v_mov_b64_e32 v[8:9], 0
	v_mov_b64_e32 v[10:11], 0
	v_mov_b64_e32 v[12:13], 0
	v_mov_b64_e32 v[14:15], 0
	v_mov_b64_e32 v[24:25], 0
	v_mov_b64_e32 v[26:27], 0
	v_mov_b64_e32 v[28:29], 0
	v_mov_b64_e32 v[30:31], 0
	v_mov_b64_e32 v[40:41], 0
	v_mov_b64_e32 v[42:43], 0
	v_mov_b64_e32 v[44:45], 0
	v_mov_b64_e32 v[46:47], 0
	v_mov_b64_e32 v[56:57], 0
	v_mov_b64_e32 v[58:59], 0
	v_mov_b64_e32 v[60:61], 0
	v_mov_b64_e32 v[62:63], 0
	v_mov_b64_e32 v[64:65], 0
	v_mov_b64_e32 v[66:67], 0
	v_mov_b64_e32 v[68:69], 0
	v_mov_b64_e32 v[70:71], 0
	v_mov_b64_e32 v[80:81], 0
	v_mov_b64_e32 v[82:83], 0
	v_mov_b64_e32 v[84:85], 0
	v_mov_b64_e32 v[86:87], 0
	v_mov_b64_e32 v[96:97], 0
	v_mov_b64_e32 v[98:99], 0
	v_mov_b64_e32 v[100:101], 0
	v_mov_b64_e32 v[102:103], 0
	v_mov_b64_e32 v[112:113], 0
	v_mov_b64_e32 v[114:115], 0
	v_mov_b64_e32 v[116:117], 0
	v_mov_b64_e32 v[118:119], 0
	v_mov_b64_e32 v[72:73], 0
	v_mov_b64_e32 v[74:75], 0
	v_mov_b64_e32 v[76:77], 0
	v_mov_b64_e32 v[78:79], 0
	v_mov_b64_e32 v[88:89], 0
	v_mov_b64_e32 v[90:91], 0
	v_mov_b64_e32 v[92:93], 0
	v_mov_b64_e32 v[94:95], 0
	v_mov_b64_e32 v[104:105], 0
	v_mov_b64_e32 v[106:107], 0
	v_mov_b64_e32 v[108:109], 0
	v_mov_b64_e32 v[110:111], 0
	v_mov_b64_e32 v[120:121], 0
	v_mov_b64_e32 v[122:123], 0
	v_mov_b64_e32 v[124:125], 0
	v_mov_b64_e32 v[126:127], 0
